# out-proj GEMM K-loop also on scalar bases + invariant VGPR offsets; cumulative with g6
# baseline (speedup 1.0000x reference)
; DI int otid() { int t = threadIdx.x; asm volatile("" : "+v"(t)); return t; }
; DI f32x16 fzero() { f32x16 z; for (int i = 0; i < 16; ++i) z[i] = 0.f; return z; }
; template <int TJ>
; DI void gemm_core(const u16* __restrict__ W, int ldw, const u16* __restrict__ X, int ldx, int K, f32x16 (&acc)[2][TJ], char* lds) {
;     ...
;   const int tid = otid(), lane = tid & 63, wid = tid >> 6, r = lane & 31, h = lane >> 5;
;   const int wn = wid & 1, wt = wid >> 1;
;   u32x4 wA[2], xA[TJ], wB[2], xB[TJ];
;   const int lrow = tid >> 2, lch = tid & 3;
;   const u16* wp = W + (size_t)lrow * ldw + lch * 8;
;   const u16* xp = X + (size_t)lrow * ldx + lch * 8;
;   const int nk = K / 32;
;     ...
;   G_LOAD(wA, xA, 0);
;   G_LOAD(wB, xB, 1);
;   G_STORE(wA, xA, 0);
; template <int TJ>
; DI void out_tile(const Params& p, int layer, size_t t0, int nt, char* lds) {
;   const u16* Wo = (const u16*)(p.ws + OFF_WO); u16* P = (u16*)(p.ws + OFF_P);
;   const float* mod = (const float*)(p.ws + OFF_SMALL + SM_MOD) + (size_t)layer * 9 * 3072;
;   const int tid = otid(), lane = tid & 63, wid = tid >> 6, h = lane >> 5;
;   const int wn = wid & 1;
;   f32x16 acc[2][TJ];
; #pragma unroll
;   for (int i = 0; i < 2; ++i)
; #pragma unroll
;     for (int j = 0; j < TJ; ++j) acc[i][j] = fzero();
;   gemm_core<TJ>(Wo + (size_t)nt * 128 * 1024, 1024, P + t0 * PW, PW, 1024, acc, lds);
.LBB0_478:
	s_andn2_b64 vcc, exec, s[0:1]
	s_cbranch_vccnz .LBB0_475
	s_and_b32 s0, s36, 0xf00
	v_readlane_b32 s3, v252, 25
	s_lshl_b32 s2, s37, 5
	s_add_i32 s1, s3, s0
	s_and_b32 s0, s29, 7
	s_and_b32 s2, s2, 0xf00
	s_and_b32 s38, s37, 7
	s_lshl_b32 s0, s0, 18
	s_add_i32 s26, s3, s2
	s_lshl_b32 s2, s38, 18
	v_readlane_b32 s40, v254, 20
	v_readlane_b32 s41, v254, 21
	s_add_u32 s2, s40, s2
	v_mov_b32_e32 v182, v190
	s_addc_u32 s3, s41, 0
	s_mul_i32 s39, s26, 0x2e40
	v_mov_b32_e32 v16, v190
	s_add_u32 s40, s22, s39
	s_addc_u32 s41, s23, 0
	v_ashrrev_i32_e32 v0, 2, v16
	v_ashrrev_i32_e32 v1, 31, v0
	v_and_b32_e32 v17, 3, v16
	v_lshlrev_b64 v[2:3], 11, v[0:1]
	v_mov_b64_e32 v[6:7], s[40:41]
	v_lshl_add_u64 v[4:5], s[2:3], 0, v[2:3]
	s_mov_b64 s[42:43], s[2:3]
	s_add_u32 s44, s2, 0x20000
	s_addc_u32 s45, s3, 0
	s_mov_b64 s[46:47], s[40:41]
	s_add_u32 s50, s40, 0xb9000
	s_addc_u32 s51, s41, 0
	s_add_u32 s52, s40, 0x172000
	s_addc_u32 s53, s41, 0
	s_add_u32 s54, s40, 0x22b000
	s_addc_u32 s55, s41, 0
	s_waitcnt vmcnt(4)
	v_lshlrev_b32_e32 v64, 4, v17
	v_mad_i64_i32 v[6:7], s[2:3], v0, s89, v[6:7]
	v_lshl_add_u64 v[4:5], v[4:5], 0, v[64:65]
	v_add_u32_e32 v178, v2, v64
	v_mul_u32_u24_e32 v179, 0x2e40, v0
	v_add_u32_e32 v179, v179, v64
	s_mov_b32 s2, 0x20000
	v_add_co_u32_e32 v8, vcc, s2, v4
	v_lshl_add_u64 v[6:7], v[6:7], 0, v[64:65]
	s_nop 0
	v_addc_co_u32_e32 v9, vcc, 0, v5, vcc
	v_add_co_u32_e32 v10, vcc, s25, v6
	s_mov_b32 s2, 0x172000
	s_nop 0
	v_addc_co_u32_e32 v11, vcc, 0, v7, vcc
	v_add_co_u32_e32 v12, vcc, s2, v6
	s_mov_b32 s2, 0x22b000
	s_nop 0
	v_addc_co_u32_e32 v13, vcc, 0, v7, vcc
	v_add_co_u32_e32 v14, vcc, s2, v6
	global_load_dwordx4 v[130:133], v[4:5], off
	global_load_dwordx4 v[138:141], v[6:7], off
	v_addc_co_u32_e32 v15, vcc, 0, v7, vcc
	global_load_dwordx4 v[134:137], v[8:9], off
	global_load_dwordx4 v[142:145], v[10:11], off
	global_load_dwordx4 v[146:149], v[12:13], off
	global_load_dwordx4 v[150:153], v[14:15], off
	global_load_dwordx4 v[154:157], v[4:5], off offset:64
	global_load_dwordx4 v[158:161], v[8:9], off offset:64
	global_load_dwordx4 v[162:165], v[6:7], off offset:64
	global_load_dwordx4 v[166:169], v[10:11], off offset:64
	global_load_dwordx4 v[170:173], v[12:13], off offset:64
	global_load_dwordx4 v[174:177], v[14:15], off offset:64
	v_bfe_u32 v1, v16, 5, 1
	v_lshlrev_b32_e32 v16, 4, v16
	v_lshlrev_b32_e32 v18, 11, v17
	v_lshlrev_b32_e32 v17, 5, v17
	v_lshlrev_b32_e32 v19, 4, v0
	v_lshlrev_b32_e32 v20, 11, v1
	v_lshlrev_b32_e32 v21, 5, v1
	v_or_b32_e32 v1, 2, v1
	s_mulk_i32 s1, 0x2e40
	v_and_b32_e32 v22, 0x5f0, v16
	v_xor_b32_e32 v23, v19, v17
	v_add_u32_e32 v24, 0x400, v19
	v_add_u32_e32 v25, v18, v18
	v_add_u32_e32 v26, 0x800, v19
	v_add_u32_e32 v19, 0xc00, v19
	s_movk_i32 s2, 0x200
	v_and_b32_e32 v4, 0xfffff9f0, v16
	v_lshlrev_b32_e32 v10, 11, v1
	v_lshlrev_b32_e32 v1, 5, v1
	v_bitop3_b32 v28, v22, v21, s2 bitop3:0x36
	v_add_u32_e32 v183, v18, v23
	v_xor_b32_e32 v24, v24, v17
	v_add_u32_e32 v184, v25, v23
	v_xor_b32_e32 v23, v26, v17
	v_xor_b32_e32 v17, v19, v17
	v_bitop3_b32 v7, v4, v21, s2 bitop3:0x36
	s_movk_i32 s3, 0x400
	v_bitop3_b32 v12, v1, v22, s2 bitop3:0x1e
	v_bitop3_b32 v15, v1, v4, s2 bitop3:0x1e
	s_add_u32 s2, s22, s1
	v_add_u32_e32 v188, v25, v17
	v_bitop3_b32 v8, v4, v21, s3 bitop3:0x36
	v_bitop3_b32 v17, v1, v4, s3 bitop3:0x1e
	s_addc_u32 s3, s23, 0
	s_movk_i32 s18, 0x5f0
	s_movk_i32 s19, 0xf9f0
	s_movk_i32 s39, 0x600
	v_mov_b64_e32 v[4:5], s[2:3]
	s_add_u32 s0, s22, s0
	v_bitop3_b32 v27, v21, v16, s18 bitop3:0x78
	v_add_u32_e32 v29, v20, v20
	v_bitop3_b32 v6, v21, v16, s19 bitop3:0x78
	v_bitop3_b32 v9, v21, v16, s39 bitop3:0x1e
	v_bitop3_b32 v11, v1, v16, s18 bitop3:0x78
	v_add_u32_e32 v13, v10, v10
	v_bitop3_b32 v14, v1, v16, s19 bitop3:0x78
	v_bitop3_b32 v1, v1, v16, s39 bitop3:0x1e
	s_nop 0
	s_addc_u32 s1, s23, 0
	v_mov_b32_e32 v0, 0
	v_add_u32_e32 v185, v18, v24
	v_add_u32_e32 v186, v25, v24
	v_add_u32_e32 v187, v25, v23
	s_nop 0
	s_mov_b32 s39, -2
	v_add_u32_e32 v189, v20, v27
	v_add_u32_e32 v214, v20, v28
	v_add_u32_e32 v215, v29, v6
	v_add_u32_e32 v216, v29, v7
	v_add_u32_e32 v217, v29, v8
	v_add_u32_e32 v218, v29, v9
	v_add_u32_e32 v219, v10, v11
	v_add_u32_e32 v220, v10, v12
	v_add_u32_e32 v221, v13, v14
	v_add_u32_e32 v222, v13, v15
	v_add_u32_e32 v223, v13, v17
	v_add_u32_e32 v224, v13, v1
	v_mov_b32_e32 v1, v0
	v_mov_b32_e32 v2, v0
	v_mov_b32_e32 v3, v0
	v_mov_b32_e32 v4, v0
	v_mov_b32_e32 v5, v0
	v_mov_b32_e32 v6, v0
	v_mov_b32_e32 v7, v0
	v_mov_b32_e32 v8, v0
	v_mov_b32_e32 v9, v0
	v_mov_b32_e32 v10, v0
	v_mov_b32_e32 v11, v0
	v_mov_b32_e32 v12, v0
	v_mov_b32_e32 v13, v0
	v_mov_b32_e32 v14, v0
	v_mov_b32_e32 v15, v0
	v_mov_b32_e32 v32, v0
	v_mov_b32_e32 v33, v0
	v_mov_b32_e32 v34, v0
	v_mov_b32_e32 v35, v0
	v_mov_b32_e32 v36, v0
	v_mov_b32_e32 v37, v0
	v_mov_b32_e32 v38, v0
	v_mov_b32_e32 v39, v0
	v_mov_b32_e32 v40, v0
	v_mov_b32_e32 v41, v0
	v_mov_b32_e32 v42, v0
	v_mov_b32_e32 v43, v0
	v_mov_b32_e32 v44, v0
	v_mov_b32_e32 v45, v0
	v_mov_b32_e32 v46, v0
	v_mov_b32_e32 v47, v0
	v_mov_b32_e32 v66, v0
	v_mov_b32_e32 v67, v0
	v_mov_b32_e32 v68, v0
	v_mov_b32_e32 v69, v0
	v_mov_b32_e32 v70, v0
	v_mov_b32_e32 v71, v0
	v_mov_b32_e32 v72, v0
	v_mov_b32_e32 v73, v0
	v_mov_b32_e32 v74, v0
	v_mov_b32_e32 v75, v0
	v_mov_b32_e32 v76, v0
	v_mov_b32_e32 v77, v0
	v_mov_b32_e32 v78, v0
	v_mov_b32_e32 v79, v0
	v_mov_b32_e32 v80, v0
	v_mov_b32_e32 v81, v0
	v_mov_b32_e32 v98, v0
	v_mov_b32_e32 v99, v0
	v_mov_b32_e32 v100, v0
	v_mov_b32_e32 v101, v0
	v_mov_b32_e32 v102, v0
	v_mov_b32_e32 v103, v0
	v_mov_b32_e32 v104, v0
	v_mov_b32_e32 v105, v0
	v_mov_b32_e32 v106, v0
	v_mov_b32_e32 v107, v0
; template <int TJ>
; DI void gemm_core(const u16* __restrict__ W, int ldw, const u16* __restrict__ X, int ldx, int K, f32x16 (&acc)[2][TJ], char* lds) {
;     ...
;   G_LOAD(wA, xA, 0);
;   G_LOAD(wB, xB, 1);
;   G_STORE(wA, xA, 0);
;   __syncthreads();
;   for (int kt = 0; kt < nk; kt += 2) {
;     if (kt + 2 < nk) G_LOAD(wA, xA, kt + 2);
;     G_COMPUTE(0);
;     G_STORE(wB, xB, 1);
;     __syncthreads();
;     if (kt + 3 < nk) G_LOAD(wB, xB, kt + 3);
;     G_COMPUTE(1);
;     if (kt + 2 < nk) G_STORE(wA, xA, 0);
;     __syncthreads();
;   }
	v_mov_b32_e32 v108, v0
	v_mov_b32_e32 v109, v0
	v_mov_b32_e32 v110, v0
	v_mov_b32_e32 v111, v0
	v_mov_b32_e32 v112, v0
	v_mov_b32_e32 v113, v0
	v_mov_b32_e32 v16, v0
	v_mov_b32_e32 v17, v0
	v_mov_b32_e32 v18, v0
	v_mov_b32_e32 v19, v0
	v_mov_b32_e32 v20, v0
	v_mov_b32_e32 v21, v0
	v_mov_b32_e32 v22, v0
	v_mov_b32_e32 v23, v0
	v_mov_b32_e32 v24, v0
	v_mov_b32_e32 v25, v0
	v_mov_b32_e32 v26, v0
	v_mov_b32_e32 v27, v0
	v_mov_b32_e32 v28, v0
	v_mov_b32_e32 v29, v0
	v_mov_b32_e32 v30, v0
	v_mov_b32_e32 v31, v0
	v_mov_b32_e32 v48, v0
	v_mov_b32_e32 v49, v0
	v_mov_b32_e32 v50, v0
	v_mov_b32_e32 v51, v0
	v_mov_b32_e32 v52, v0
	v_mov_b32_e32 v53, v0
	v_mov_b32_e32 v54, v0
	v_mov_b32_e32 v55, v0
	v_mov_b32_e32 v56, v0
	v_mov_b32_e32 v57, v0
	v_mov_b32_e32 v58, v0
	v_mov_b32_e32 v59, v0
	v_mov_b32_e32 v60, v0
	v_mov_b32_e32 v61, v0
	v_mov_b32_e32 v62, v0
	v_mov_b32_e32 v63, v0
	v_mov_b32_e32 v82, v0
	v_mov_b32_e32 v83, v0
	v_mov_b32_e32 v84, v0
	v_mov_b32_e32 v85, v0
	v_mov_b32_e32 v86, v0
	v_mov_b32_e32 v87, v0
	v_mov_b32_e32 v88, v0
	v_mov_b32_e32 v89, v0
	v_mov_b32_e32 v90, v0
	v_mov_b32_e32 v91, v0
	v_mov_b32_e32 v92, v0
	v_mov_b32_e32 v93, v0
	v_mov_b32_e32 v94, v0
	v_mov_b32_e32 v95, v0
	v_mov_b32_e32 v96, v0
	v_mov_b32_e32 v97, v0
	v_mov_b32_e32 v114, v0
	v_mov_b32_e32 v115, v0
	v_mov_b32_e32 v116, v0
	v_mov_b32_e32 v117, v0
	v_mov_b32_e32 v118, v0
	v_mov_b32_e32 v119, v0
	v_mov_b32_e32 v120, v0
	v_mov_b32_e32 v121, v0
	v_mov_b32_e32 v122, v0
	v_mov_b32_e32 v123, v0
	v_mov_b32_e32 v124, v0
	v_mov_b32_e32 v125, v0
	v_mov_b32_e32 v126, v0
	v_mov_b32_e32 v127, v0
	v_mov_b32_e32 v128, v0
	v_mov_b32_e32 v129, v0
	s_waitcnt vmcnt(11)
	ds_write_b128 v183, v[130:133]
	s_waitcnt vmcnt(9)
	ds_write_b128 v185, v[134:137]
	ds_write_b128 v184, v[138:141] offset:8192
	s_waitcnt vmcnt(8)
	ds_write_b128 v186, v[142:145] offset:8192
	s_waitcnt vmcnt(7)
	ds_write_b128 v187, v[146:149] offset:8192
	s_waitcnt vmcnt(6)
	ds_write_b128 v188, v[150:153] offset:8192
	s_waitcnt lgkmcnt(0)
	s_barrier
	s_branch .LBB0_481
.LBB0_480:
	s_add_u32 s42, s42, 0x80
	s_addc_u32 s43, s43, 0
	s_add_u32 s44, s44, 0x80
	s_addc_u32 s45, s45, 0
	s_add_u32 s46, s46, 0x80
	s_addc_u32 s47, s47, 0
	s_add_u32 s50, s50, 0x80
	s_addc_u32 s51, s51, 0
	s_add_u32 s52, s52, 0x80
	s_addc_u32 s53, s53, 0
	s_add_u32 s54, s54, 0x80
	s_addc_u32 s55, s55, 0
	s_andn2_b64 vcc, exec, s[0:1]
	s_waitcnt lgkmcnt(0)
	s_barrier
	s_cbranch_vccz .LBB0_474
.LBB0_481:
	s_add_i32 s39, s39, 2
	s_cmp_lt_u32 s39, 30
	s_cselect_b64 s[2:3], -1, 0
	s_cmp_gt_u32 s39, 29
	s_cselect_b64 s[0:1], -1, 0
	ds_read_b128 v[206:209], v189
	ds_read_b128 v[226:229], v214
	ds_read_b128 v[230:233], v215 offset:8192
	ds_read_b128 v[234:237], v216 offset:8192
	ds_read_b128 v[238:241], v217 offset:8192
	ds_read_b128 v[242:245], v218 offset:8192
	ds_read_b128 v[130:133], v219
	ds_read_b128 v[134:137], v220
	ds_read_b128 v[138:141], v221 offset:8192
	ds_read_b128 v[142:145], v222 offset:8192
	ds_read_b128 v[146:149], v223 offset:8192
	ds_read_b128 v[150:153], v224 offset:8192
	s_setprio 1
	s_waitcnt lgkmcnt(9)
	v_mfma_f32_32x32x16_bf16 v[114:129], v[206:209], v[230:233], v[114:129]
	s_waitcnt lgkmcnt(8)
	v_mfma_f32_32x32x16_bf16 v[82:97], v[206:209], v[234:237], v[82:97]
	s_waitcnt lgkmcnt(7)
	v_mfma_f32_32x32x16_bf16 v[48:63], v[206:209], v[238:241], v[48:63]
	s_waitcnt lgkmcnt(6)
	v_mfma_f32_32x32x16_bf16 v[16:31], v[206:209], v[242:245], v[16:31]
	v_mfma_f32_32x32x16_bf16 v[98:113], v[226:229], v[230:233], v[98:113]
	v_mfma_f32_32x32x16_bf16 v[66:81], v[226:229], v[234:237], v[66:81]
	v_mfma_f32_32x32x16_bf16 v[32:47], v[226:229], v[238:241], v[32:47]
	v_mfma_f32_32x32x16_bf16 v[0:15], v[226:229], v[242:245], v[0:15]
	s_setprio 0
	s_waitcnt vmcnt(0)
	ds_write_b128 v183, v[154:157] offset:24576
	ds_write_b128 v185, v[158:161] offset:24576
	ds_write_b128 v184, v[162:165] offset:32768
	ds_write_b128 v186, v[166:169] offset:32768
	ds_write_b128 v187, v[170:173] offset:32768
	ds_write_b128 v188, v[174:177] offset:32768
	s_and_b64 vcc, exec, s[0:1]
	s_cbranch_vccnz .Lgl_op_skipA
	global_load_dwordx4 v[154:157], v178, s[42:43] offset:128
	global_load_dwordx4 v[158:161], v178, s[44:45] offset:128
	global_load_dwordx4 v[162:165], v179, s[46:47] offset:128
	global_load_dwordx4 v[166:169], v179, s[50:51] offset:128
	global_load_dwordx4 v[170:173], v179, s[52:53] offset:128
	global_load_dwordx4 v[174:177], v179, s[54:55] offset:128
.Lgl_op_skipA:
	s_waitcnt lgkmcnt(6)
	s_setprio 1
	v_mfma_f32_32x32x16_bf16 v[114:129], v[130:133], v[138:141], v[114:129]
	v_mfma_f32_32x32x16_bf16 v[82:97], v[130:133], v[142:145], v[82:97]
	v_mfma_f32_32x32x16_bf16 v[48:63], v[130:133], v[146:149], v[48:63]
	v_mfma_f32_32x32x16_bf16 v[16:31], v[130:133], v[150:153], v[16:31]
	v_mfma_f32_32x32x16_bf16 v[98:113], v[134:137], v[138:141], v[98:113]
	v_mfma_f32_32x32x16_bf16 v[66:81], v[134:137], v[142:145], v[66:81]
	v_mfma_f32_32x32x16_bf16 v[32:47], v[134:137], v[146:149], v[32:47]
	v_mfma_f32_32x32x16_bf16 v[0:15], v[134:137], v[150:153], v[0:15]
	s_setprio 0
	s_waitcnt lgkmcnt(0)
	s_barrier
	ds_read_b128 v[206:209], v189 offset:24576
	ds_read_b128 v[226:229], v214 offset:24576
	ds_read_b128 v[230:233], v215 offset:32768
	ds_read_b128 v[234:237], v216 offset:32768
	ds_read_b128 v[238:241], v217 offset:32768
	ds_read_b128 v[242:245], v218 offset:32768
	ds_read_b128 v[130:133], v219 offset:24576
	ds_read_b128 v[134:137], v220 offset:24576
	ds_read_b128 v[138:141], v221 offset:32768
	ds_read_b128 v[142:145], v222 offset:32768
	ds_read_b128 v[146:149], v223 offset:32768
	ds_read_b128 v[150:153], v224 offset:32768
	s_setprio 1
	s_waitcnt lgkmcnt(9)
	v_mfma_f32_32x32x16_bf16 v[114:129], v[206:209], v[230:233], v[114:129]
	s_waitcnt lgkmcnt(8)
	v_mfma_f32_32x32x16_bf16 v[82:97], v[206:209], v[234:237], v[82:97]
	s_waitcnt lgkmcnt(7)
	v_mfma_f32_32x32x16_bf16 v[48:63], v[206:209], v[238:241], v[48:63]
	s_waitcnt lgkmcnt(6)
	v_mfma_f32_32x32x16_bf16 v[16:31], v[206:209], v[242:245], v[16:31]
	v_mfma_f32_32x32x16_bf16 v[98:113], v[226:229], v[230:233], v[98:113]
	v_mfma_f32_32x32x16_bf16 v[66:81], v[226:229], v[234:237], v[66:81]
	v_mfma_f32_32x32x16_bf16 v[32:47], v[226:229], v[238:241], v[32:47]
	v_mfma_f32_32x32x16_bf16 v[0:15], v[226:229], v[242:245], v[0:15]
	s_setprio 0
	s_and_b64 vcc, exec, s[0:1]
	s_cbranch_vccnz .Lgl_op_lastB
	s_waitcnt vmcnt(0)
	ds_write_b128 v183, v[154:157]
	ds_write_b128 v185, v[158:161]
	ds_write_b128 v184, v[162:165] offset:8192
	ds_write_b128 v186, v[166:169] offset:8192
	ds_write_b128 v187, v[170:173] offset:8192
	ds_write_b128 v188, v[174:177] offset:8192
	global_load_dwordx4 v[154:157], v178, s[42:43] offset:192
	global_load_dwordx4 v[158:161], v178, s[44:45] offset:192
	global_load_dwordx4 v[162:165], v179, s[46:47] offset:192
	global_load_dwordx4 v[166:169], v179, s[50:51] offset:192
	global_load_dwordx4 v[170:173], v179, s[52:53] offset:192
	global_load_dwordx4 v[174:177], v179, s[54:55] offset:192
	s_waitcnt lgkmcnt(6)
	s_branch .Lgl_op_m2
